# v25 plus nt cache hint on the P1 row-phase x loads (streamed once) so the converted weights stay cache resident for the in-projection GEMM
# baseline (speedup 1.0000x reference)
; template <bool FINAL>
; __device__ __forceinline__ void rows_phase(const float* srcL, const float* srcC, int nL, int nTot, const float* g, const float* mod, int sh_off, int sc_off, void* dst, int gw, int NGW, int lane) {
;     asm volatile("" : "+v"(lane));
;     const int per = (nTot + NGW - 1) / NGW; const int r0 = gw * per; int r1 = r0 + per; if (r1 > nTot) r1 = nTot;
;     if (r0 >= r1) return;
;     f32x4 v[8], A[8], B[8]; int cur = -1;
;     { const float* p = (r0 < nL ? srcL + (size_t)r0 * DM : srcC + (size_t)(r0 - nL) * DM) + lane * 4;
; #pragma unroll
;       for (int j = 0; j < 8; ++j) v[j] = *(const f32x4*)(p + j * 256); }
; #pragma unroll 1
;     for (int row = r0; row < r1; ++row) {
;         f32x4 vn[8];
;         const bool more = row + 1 < r1;
;         if (more) { const int rn = row + 1; const float* p = (rn < nL ? srcL + (size_t)rn * DM : srcC + (size_t)(rn - nL) * DM) + lane * 4;
; #pragma unroll
;             for (int j = 0; j < 8; ++j) vn[j] = *(const f32x4*)(p + j * 256); }
.LBB0_121:
	s_or_b64 exec, exec, s[0:1]
	s_abs_i32 s6, s96
	v_cvt_f32_u32_e32 v1, s6
	s_add_i32 s0, s96, 0x47ff
	s_ashr_i32 s1, s0, 31
	s_ashr_i32 s3, s96, 31
	v_rcp_iflag_f32_e32 v1, v1
	v_writelane_b32 v242, s3, 27
	s_xor_b32 s1, s1, s3
	s_sub_i32 s3, 0xffffb801, s96
	v_mul_f32_e32 v1, 0x4f7ffffe, v1
	v_cvt_u32_f32_e32 v1, v1
	s_max_i32 s0, s0, s3
	s_sub_i32 s3, 0, s6
	s_waitcnt lgkmcnt(0)
	v_mov_b32_e32 v0, v177
	v_readfirstlane_b32 s4, v1
	s_mul_i32 s3, s3, s4
	s_mul_hi_u32 s3, s4, s3
	s_add_i32 s3, s4, s3
	v_writelane_b32 v242, s3, 28
	s_mul_hi_u32 s3, s0, s3
	s_mul_i32 s4, s3, s6
	s_sub_i32 s0, s0, s4
	s_add_i32 s4, s3, 1
	s_sub_i32 s5, s0, s6
	s_cmp_ge_u32 s0, s6
	s_cselect_b32 s3, s4, s3
	s_cselect_b32 s0, s5, s0
	s_add_i32 s4, s3, 1
	s_cmp_ge_u32 s0, s6
	s_cselect_b32 s0, s4, s3
	s_xor_b32 s0, s0, s1
	s_sub_i32 s1, s0, s1
	s_mul_i32 s0, s1, s93
	s_add_i32 s1, s0, s1
	s_min_i32 s3, s1, 0x4800
	s_cmp_ge_i32 s0, s3
	v_mbcnt_lo_u32_b32 v198, -1, 0
	s_barrier
	v_writelane_b32 v242, s6, 29
	s_cbranch_scc1 .LBB0_130
	s_add_i32 s4, s0, 0xffffc000
	s_ashr_i32 s1, s0, 31
	s_cmpk_lt_i32 s0, 0x4000
	v_readlane_b32 s8, v242, 11
	s_cselect_b32 s5, s1, 0
	s_cselect_b32 s4, s0, s4
	v_readlane_b32 s9, v242, 12
	v_readlane_b32 s12, v242, 15
	v_readlane_b32 s13, v242, 16
	s_cselect_b32 s6, s9, s13
	s_cselect_b32 s7, s8, s12
	s_lshl_b64 s[4:5], s[4:5], 13
	v_lshlrev_b32_e32 v128, 2, v0
	s_add_u32 s4, s7, s4
	v_ashrrev_i32_e32 v129, 31, v128
	s_addc_u32 s5, s6, s5
	v_lshlrev_b64 v[44:45], 2, v[128:129]
	v_lshl_add_u64 v[8:9], s[4:5], 0, v[44:45]
	global_load_dwordx4 v[40:43], v[8:9], off nt
	global_load_dwordx4 v[32:35], v[8:9], off offset:1024 nt
	s_movk_i32 s6, 0x1000
	v_add_co_u32_e32 v10, vcc, s6, v8
	v_mbcnt_hi_u32_b32 v46, -1, v198
	s_nop 0
	v_addc_co_u32_e32 v11, vcc, 0, v9, vcc
	global_load_dwordx4 v[4:7], v[10:11], off offset:2048 nt
	global_load_dwordx4 v[0:3], v[10:11], off offset:3072 nt
	global_load_dwordx4 v[36:39], v[8:9], off offset:2048 nt
	global_load_dwordx4 v[28:31], v[8:9], off offset:3072 nt
	global_load_dwordx4 v[24:27], v[10:11], off nt
	global_load_dwordx4 v[20:23], v[10:11], off offset:1024 nt
	v_and_b32_e32 v47, 64, v46
	v_xor_b32_e32 v52, 1, v46
	v_add_u32_e32 v47, 64, v47
	v_xor_b32_e32 v53, 2, v46
	v_cmp_lt_i32_e32 vcc, v52, v47
	v_readlane_b32 s10, v242, 13
	v_readlane_b32 s11, v242, 14
	v_readlane_b32 s20, v242, 23
	v_readlane_b32 s21, v242, 24
	v_xor_b32_e32 v54, 4, v46
	v_cndmask_b32_e32 v52, v46, v52, vcc
	v_cmp_lt_i32_e32 vcc, v53, v47
	s_mov_b64 s[10:11], 0x1400
	v_xor_b32_e32 v55, 8, v46
	v_cndmask_b32_e32 v53, v46, v53, vcc
	v_cmp_lt_i32_e32 vcc, v54, v47
	v_lshl_add_u64 v[130:131], s[20:21], 0, v[44:45]
	v_xor_b32_e32 v56, 16, v46
	v_cndmask_b32_e32 v54, v46, v54, vcc
	v_cmp_lt_i32_e32 vcc, v55, v47
	v_lshl_add_u64 v[136:137], v[130:131], 0, s[10:11]
	s_lshl_b64 s[10:11], s[0:1], 12
	v_xor_b32_e32 v57, 32, v46
	v_cndmask_b32_e32 v55, v46, v55, vcc
	v_cmp_lt_i32_e32 vcc, v56, v47
	s_add_u32 s10, s28, s10
	v_readlane_b32 s14, v242, 17
	v_readlane_b32 s15, v242, 18
	v_readlane_b32 s16, v242, 19
	v_readlane_b32 s17, v242, 20
	v_cndmask_b32_e32 v56, v46, v56, vcc
	v_cmp_lt_i32_e32 vcc, v57, v47
	s_addc_u32 s11, s29, s11
	s_mov_b64 s[4:5], 0x1000
	s_mov_b64 s[12:13], 0x1800
	s_mov_b64 s[14:15], 0x1c00
	s_mov_b64 s[16:17], 0xdb00000
	v_cndmask_b32_e32 v46, v46, v57, vcc
	v_lshl_add_u64 v[132:133], s[28:29], 0, v[44:45]
	v_lshl_add_u64 v[44:45], v[128:129], 1, s[10:11]
	s_mov_b32 s9, -1
	s_movk_i32 s7, 0x3000
	v_mov_b32_e32 v144, 0x358637bd
	s_mov_b32 s8, 0xf800000
	v_mov_b32_e32 v145, 0x260
	v_mov_b32_e32 v146, 0xc000
	v_lshlrev_b32_e32 v147, 2, v52
	v_lshlrev_b32_e32 v148, 2, v53
	v_lshlrev_b32_e32 v149, 2, v54
	v_lshlrev_b32_e32 v150, 2, v55
	v_lshlrev_b32_e32 v151, 2, v56
	v_lshlrev_b32_e32 v152, 2, v46
	v_lshl_add_u64 v[134:135], v[130:131], 0, s[4:5]
	v_lshl_add_u64 v[138:139], v[130:131], 0, s[12:13]
	v_lshl_add_u64 v[140:141], v[130:131], 0, s[14:15]
	v_lshl_add_u64 v[142:143], v[44:45], 0, s[16:17]
	v_readlane_b32 s18, v242, 21
	v_readlane_b32 s19, v242, 22
	v_readlane_b32 s22, v242, 25
	v_readlane_b32 s23, v242, 26
	s_waitcnt vmcnt(4)
	v_mov_b32_e32 v153, v0
	v_mov_b32_e32 v154, v1
	v_mov_b32_e32 v155, v2
	v_mov_b32_e32 v156, v3
	s_branch .LBB0_124

; template <bool FINAL>
; __device__ __forceinline__ void rows_phase(const float* srcL, const float* srcC, int nL, int nTot, const float* g, const float* mod, int sh_off, int sc_off, void* dst, int gw, int NGW, int lane) {
;     ...
;     for (int row = r0; row < r1; ++row) {
;         f32x4 vn[8];
;         const bool more = row + 1 < r1;
;         if (more) { const int rn = row + 1; const float* p = (rn < nL ? srcL + (size_t)rn * DM : srcC + (size_t)(rn - nL) * DM) + lane * 4;
; #pragma unroll
;             for (int j = 0; j < 8; ++j) vn[j] = *(const f32x4*)(p + j * 256); }
;         const int mr = FINAL ? 0 : (row < nL ? (row >> 11) : 8);
;         if (mr != cur) { cur = mr;
.LBB0_128:
	s_add_i32 s1, s0, 0xffffc001
	v_readlane_b32 s48, v242, 11
	s_cmpk_lt_i32 s0, 0x3fff
	v_readlane_b32 s49, v242, 12
	v_readlane_b32 s52, v242, 15
	v_readlane_b32 s53, v242, 16
	s_cselect_b32 s13, s11, 0
	s_cselect_b32 s12, s10, s1
	s_mov_b64 s[16:17], s[48:49]
	s_mov_b64 s[20:21], s[52:53]
	s_cselect_b32 s1, s17, s21
	s_cselect_b32 s16, s16, s20
	s_lshl_b64 s[12:13], s[12:13], 13
	s_add_u32 s12, s16, s12
	s_addc_u32 s13, s1, s13
	v_lshl_add_u64 v[88:89], v[128:129], 2, s[12:13]
	global_load_dwordx4 v[84:87], v[88:89], off nt
	global_load_dwordx4 v[80:83], v[88:89], off offset:1024 nt
	global_load_dwordx4 v[76:79], v[88:89], off offset:2048 nt
	global_load_dwordx4 v[72:75], v[88:89], off offset:3072 nt
	v_add_co_u32_e32 v88, vcc, 0x1000, v88
	v_readlane_b32 s50, v242, 13
	s_nop 0
	v_addc_co_u32_e32 v89, vcc, 0, v89, vcc
	global_load_dwordx4 v[100:103], v[88:89], off nt
	global_load_dwordx4 v[96:99], v[88:89], off offset:1024 nt
	global_load_dwordx4 v[92:95], v[88:89], off offset:2048 nt
	s_nop 0
	global_load_dwordx4 v[88:91], v[88:89], off offset:3072 nt
	v_readlane_b32 s51, v242, 14
	v_readlane_b32 s54, v242, 17
	v_readlane_b32 s55, v242, 18
	v_readlane_b32 s56, v242, 19
	v_readlane_b32 s57, v242, 20
	v_readlane_b32 s58, v242, 21
	v_readlane_b32 s59, v242, 22
	v_readlane_b32 s60, v242, 23
	v_readlane_b32 s61, v242, 24
	v_readlane_b32 s62, v242, 25
	v_readlane_b32 s63, v242, 26
	s_min_i32 s0, s0, 0x4000
	s_ashr_i32 s0, s0, 11
	s_cmp_eq_u32 s0, s9
	s_cbranch_scc1 .LBB0_123
